# v8: hand re-scheduled A-fragment double-buffering in outproj0 and q-up/kv-up GEMM k-loops (uses free v248-251)
# speedup vs baseline: 1.0100x; 1.0100x over previous
; #define MFMA(a, b, c) __builtin_amdgcn_mfma_f32_32x32x16_bf16((a), (b), (c), 0, 0, 0)
; template <int AMODE, int BN, class Epi>
; __device__ __forceinline__ void gemm_tile(const bf16_t* A, const int lda, const bf16_t* Bt, const int K, const int m0, const float* mu, char* lds, const Epi& epi) {
;     ...
;   for (int kt = 0; kt < nk; ++kt) {
;     const int s = kt & 1;
;     if (kt + 1 < nk) lstore(s ^ 1, (kt + 1) * 64);
;     if (kt + 2 < nk) gload((kt + 2) * 64);
;     {
;       const char* Ab = lds + s * G_STAGE + (wm * (32 * MI) + r32) * G_LDT + hi * 16;
;       const char* Bb = lds + s * G_STAGE + 256 * G_LDT + (wn * 64 + r32) * G_LDT + hi * 16;
;       bf16x8 fb[2][2], fa[2][MI];
;       fb[0][0] = *(const bf16x8*)(Bb); fb[0][1] = *(const bf16x8*)(Bb + 32 * G_LDT);
; #pragma unroll
;       for (int mi = 0; mi < MI; ++mi) fa[0][mi] = *(const bf16x8*)(Ab + mi * 32 * G_LDT);
; #pragma unroll
;       for (int ks = 0; ks < 4; ++ks) {
;         const int sl = ks & 1;
;         if (ks + 1 < 4) {
;           fb[sl ^ 1][0] = *(const bf16x8*)(Bb + (ks + 1) * 32); fb[sl ^ 1][1] = *(const bf16x8*)(Bb + 32 * G_LDT + (ks + 1) * 32);
; #pragma unroll
;           for (int mi = 0; mi < MI; ++mi) fa[sl ^ 1][mi] = *(const bf16x8*)(Ab + mi * 32 * G_LDT + (ks + 1) * 32);
;         }
; #pragma unroll
;         for (int mi = 0; mi < MI; ++mi) { acc[mi][0] = MFMA(fb[sl][0], fa[sl][mi], acc[mi][0]); acc[mi][1] = MFMA(fb[sl][1], fa[sl][mi], acc[mi][1]); }
;       }
;     }
;     __syncthreads();
;   }
.LBB0_633:
	s_mul_i32 s23, s23, 0x12000
	s_add_i32 s23, s23, 0
	v_add3_u32 v199, s23, v235, v234
	v_add3_u32 v201, s23, v187, v234
	s_add_u32 s50, s50, 0x80
	s_addc_u32 s51, s51, 0
	s_add_i32 s10, s10, 1
	s_cmpk_lg_i32 s50, 0x800
	ds_read_b128 v[224:227], v199 offset:36864
	ds_read_b128 v[244:247], v199 offset:41472
	ds_read_b128 v[240:243], v201
	ds_read_b128 v[248:251], v201 offset:4608
	s_waitcnt lgkmcnt(1)
	v_mfma_f32_32x32x16_bf16 v[112:127], v[224:227], v[240:243], v[112:127]
	v_mfma_f32_32x32x16_bf16 v[96:111], v[244:247], v[240:243], v[96:111]
	ds_read_b128 v[240:243], v201 offset:9216
	s_waitcnt lgkmcnt(1)
	v_mfma_f32_32x32x16_bf16 v[80:95], v[224:227], v[248:251], v[80:95]
	v_mfma_f32_32x32x16_bf16 v[64:79], v[244:247], v[248:251], v[64:79]
	ds_read_b128 v[248:251], v201 offset:13824
	s_waitcnt lgkmcnt(1)
	v_mfma_f32_32x32x16_bf16 v[48:63], v[224:227], v[240:243], v[48:63]
	v_mfma_f32_32x32x16_bf16 v[32:47], v[244:247], v[240:243], v[32:47]
	ds_read_b128 v[240:243], v201 offset:32
	s_waitcnt lgkmcnt(1)
	v_mfma_f32_32x32x16_bf16 v[16:31], v[224:227], v[248:251], v[16:31]
	v_mfma_f32_32x32x16_bf16 v[0:15], v[244:247], v[248:251], v[0:15]
	ds_read_b128 v[224:227], v199 offset:36896
	ds_read_b128 v[244:247], v199 offset:41504
	ds_read_b128 v[248:251], v201 offset:4640
	s_waitcnt lgkmcnt(1)
	v_mfma_f32_32x32x16_bf16 v[112:127], v[224:227], v[240:243], v[112:127]
	v_mfma_f32_32x32x16_bf16 v[96:111], v[244:247], v[240:243], v[96:111]
	ds_read_b128 v[240:243], v201 offset:9248
	s_waitcnt lgkmcnt(1)
	v_mfma_f32_32x32x16_bf16 v[80:95], v[224:227], v[248:251], v[80:95]
	v_mfma_f32_32x32x16_bf16 v[64:79], v[244:247], v[248:251], v[64:79]
	ds_read_b128 v[248:251], v201 offset:13856
	s_waitcnt lgkmcnt(1)
	v_mfma_f32_32x32x16_bf16 v[48:63], v[224:227], v[240:243], v[48:63]
	v_mfma_f32_32x32x16_bf16 v[32:47], v[244:247], v[240:243], v[32:47]
	ds_read_b128 v[240:243], v201 offset:64
	s_waitcnt lgkmcnt(1)
	v_mfma_f32_32x32x16_bf16 v[16:31], v[224:227], v[248:251], v[16:31]
	v_mfma_f32_32x32x16_bf16 v[0:15], v[244:247], v[248:251], v[0:15]
	ds_read_b128 v[224:227], v199 offset:36928
	ds_read_b128 v[244:247], v199 offset:41536
	ds_read_b128 v[248:251], v201 offset:4672
	s_waitcnt lgkmcnt(1)
	v_mfma_f32_32x32x16_bf16 v[112:127], v[224:227], v[240:243], v[112:127]
	v_mfma_f32_32x32x16_bf16 v[96:111], v[244:247], v[240:243], v[96:111]
	ds_read_b128 v[240:243], v201 offset:9280
	s_waitcnt lgkmcnt(1)
	v_mfma_f32_32x32x16_bf16 v[80:95], v[224:227], v[248:251], v[80:95]
	v_mfma_f32_32x32x16_bf16 v[64:79], v[244:247], v[248:251], v[64:79]
	ds_read_b128 v[248:251], v201 offset:13888
	s_waitcnt lgkmcnt(1)
	v_mfma_f32_32x32x16_bf16 v[48:63], v[224:227], v[240:243], v[48:63]
	v_mfma_f32_32x32x16_bf16 v[32:47], v[244:247], v[240:243], v[32:47]
	ds_read_b128 v[240:243], v201 offset:96
	s_waitcnt lgkmcnt(1)
	v_mfma_f32_32x32x16_bf16 v[16:31], v[224:227], v[248:251], v[16:31]
	v_mfma_f32_32x32x16_bf16 v[0:15], v[244:247], v[248:251], v[0:15]
	ds_read_b128 v[224:227], v199 offset:36960
	ds_read_b128 v[244:247], v199 offset:41568
	ds_read_b128 v[248:251], v201 offset:4704
	s_waitcnt lgkmcnt(1)
	v_mfma_f32_32x32x16_bf16 v[112:127], v[224:227], v[240:243], v[112:127]
	v_mfma_f32_32x32x16_bf16 v[96:111], v[244:247], v[240:243], v[96:111]
	ds_read_b128 v[240:243], v201 offset:9312
	s_waitcnt lgkmcnt(1)
	v_mfma_f32_32x32x16_bf16 v[80:95], v[224:227], v[248:251], v[80:95]
	v_mfma_f32_32x32x16_bf16 v[64:79], v[244:247], v[248:251], v[64:79]
	ds_read_b128 v[248:251], v201 offset:13920
	s_waitcnt lgkmcnt(1)
	v_mfma_f32_32x32x16_bf16 v[48:63], v[224:227], v[240:243], v[48:63]
	v_mfma_f32_32x32x16_bf16 v[32:47], v[244:247], v[240:243], v[32:47]
	s_waitcnt lgkmcnt(0)
	s_barrier
	v_mfma_f32_32x32x16_bf16 v[16:31], v[224:227], v[248:251], v[16:31]
	v_mfma_f32_32x32x16_bf16 v[0:15], v[244:247], v[248:251], v[0:15]
	s_cbranch_scc0 .LBB0_627

; #define MFMA(a, b, c) __builtin_amdgcn_mfma_f32_32x32x16_bf16((a), (b), (c), 0, 0, 0)
; template <int AMODE, int BN, class Epi>
; __device__ __forceinline__ void gemm_tile(const bf16_t* A, const int lda, const bf16_t* Bt, const int K, const int m0, const float* mu, char* lds, const Epi& epi) {
;     ...
;   for (int kt = 0; kt < nk; ++kt) {
;     const int s = kt & 1;
;     if (kt + 1 < nk) lstore(s ^ 1, (kt + 1) * 64);
;     if (kt + 2 < nk) gload((kt + 2) * 64);
;     {
;       const char* Ab = lds + s * G_STAGE + (wm * (32 * MI) + r32) * G_LDT + hi * 16;
;       const char* Bb = lds + s * G_STAGE + 256 * G_LDT + (wn * 64 + r32) * G_LDT + hi * 16;
;       bf16x8 fb[2][2], fa[2][MI];
;       fb[0][0] = *(const bf16x8*)(Bb); fb[0][1] = *(const bf16x8*)(Bb + 32 * G_LDT);
; #pragma unroll
;       for (int mi = 0; mi < MI; ++mi) fa[0][mi] = *(const bf16x8*)(Ab + mi * 32 * G_LDT);
; #pragma unroll
;       for (int ks = 0; ks < 4; ++ks) {
;         const int sl = ks & 1;
;         if (ks + 1 < 4) {
;           fb[sl ^ 1][0] = *(const bf16x8*)(Bb + (ks + 1) * 32); fb[sl ^ 1][1] = *(const bf16x8*)(Bb + 32 * G_LDT + (ks + 1) * 32);
; #pragma unroll
;           for (int mi = 0; mi < MI; ++mi) fa[sl ^ 1][mi] = *(const bf16x8*)(Ab + mi * 32 * G_LDT + (ks + 1) * 32);
;         }
; #pragma unroll
;         for (int mi = 0; mi < MI; ++mi) { acc[mi][0] = MFMA(fb[sl][0], fa[sl][mi], acc[mi][0]); acc[mi][1] = MFMA(fb[sl][1], fa[sl][mi], acc[mi][1]); }
;       }
;     }
;     __syncthreads();
;   }
.LBB0_951:
	s_mul_i32 s19, s19, 0x12000
	s_add_i32 s19, s19, 0
	v_add3_u32 v187, s19, v210, v209
	v_add3_u32 v191, s19, v208, v209
	s_add_u32 s8, s8, 0x80
	s_addc_u32 s9, s9, 0
	s_add_i32 s6, s6, 1
	s_cmpk_eq_i32 s8, 0x300
	ds_read_b128 v[220:223], v187 offset:36864
	ds_read_b128 v[234:237], v187 offset:41472
	ds_read_b128 v[224:227], v191
	ds_read_b128 v[248:251], v191 offset:4608
	s_waitcnt lgkmcnt(1)
	v_mfma_f32_32x32x16_bf16 v[112:127], v[220:223], v[224:227], v[112:127]
	v_mfma_f32_32x32x16_bf16 v[96:111], v[234:237], v[224:227], v[96:111]
	ds_read_b128 v[224:227], v191 offset:9216
	s_waitcnt lgkmcnt(1)
	v_mfma_f32_32x32x16_bf16 v[80:95], v[220:223], v[248:251], v[80:95]
	v_mfma_f32_32x32x16_bf16 v[64:79], v[234:237], v[248:251], v[64:79]
	ds_read_b128 v[248:251], v191 offset:13824
	s_waitcnt lgkmcnt(1)
	v_mfma_f32_32x32x16_bf16 v[48:63], v[220:223], v[224:227], v[48:63]
	v_mfma_f32_32x32x16_bf16 v[32:47], v[234:237], v[224:227], v[32:47]
	ds_read_b128 v[224:227], v191 offset:32
	s_waitcnt lgkmcnt(1)
	v_mfma_f32_32x32x16_bf16 v[16:31], v[220:223], v[248:251], v[16:31]
	v_mfma_f32_32x32x16_bf16 v[0:15], v[234:237], v[248:251], v[0:15]
	ds_read_b128 v[220:223], v187 offset:36896
	ds_read_b128 v[234:237], v187 offset:41504
	ds_read_b128 v[248:251], v191 offset:4640
	s_waitcnt lgkmcnt(1)
	v_mfma_f32_32x32x16_bf16 v[112:127], v[220:223], v[224:227], v[112:127]
	v_mfma_f32_32x32x16_bf16 v[96:111], v[234:237], v[224:227], v[96:111]
	ds_read_b128 v[224:227], v191 offset:9248
	s_waitcnt lgkmcnt(1)
	v_mfma_f32_32x32x16_bf16 v[80:95], v[220:223], v[248:251], v[80:95]
	v_mfma_f32_32x32x16_bf16 v[64:79], v[234:237], v[248:251], v[64:79]
	ds_read_b128 v[248:251], v191 offset:13856
	s_waitcnt lgkmcnt(1)
	v_mfma_f32_32x32x16_bf16 v[48:63], v[220:223], v[224:227], v[48:63]
	v_mfma_f32_32x32x16_bf16 v[32:47], v[234:237], v[224:227], v[32:47]
	ds_read_b128 v[224:227], v191 offset:64
	s_waitcnt lgkmcnt(1)
	v_mfma_f32_32x32x16_bf16 v[16:31], v[220:223], v[248:251], v[16:31]
	v_mfma_f32_32x32x16_bf16 v[0:15], v[234:237], v[248:251], v[0:15]
	ds_read_b128 v[220:223], v187 offset:36928
	ds_read_b128 v[234:237], v187 offset:41536
	ds_read_b128 v[248:251], v191 offset:4672
	s_waitcnt lgkmcnt(1)
	v_mfma_f32_32x32x16_bf16 v[112:127], v[220:223], v[224:227], v[112:127]
	v_mfma_f32_32x32x16_bf16 v[96:111], v[234:237], v[224:227], v[96:111]
	ds_read_b128 v[224:227], v191 offset:9280
	s_waitcnt lgkmcnt(1)
	v_mfma_f32_32x32x16_bf16 v[80:95], v[220:223], v[248:251], v[80:95]
	v_mfma_f32_32x32x16_bf16 v[64:79], v[234:237], v[248:251], v[64:79]
	ds_read_b128 v[248:251], v191 offset:13888
	s_waitcnt lgkmcnt(1)
	v_mfma_f32_32x32x16_bf16 v[48:63], v[220:223], v[224:227], v[48:63]
	v_mfma_f32_32x32x16_bf16 v[32:47], v[234:237], v[224:227], v[32:47]
	ds_read_b128 v[224:227], v191 offset:96
	s_waitcnt lgkmcnt(1)
	v_mfma_f32_32x32x16_bf16 v[16:31], v[220:223], v[248:251], v[16:31]
	v_mfma_f32_32x32x16_bf16 v[0:15], v[234:237], v[248:251], v[0:15]
	ds_read_b128 v[220:223], v187 offset:36960
	ds_read_b128 v[234:237], v187 offset:41568
	ds_read_b128 v[248:251], v191 offset:4704
	s_waitcnt lgkmcnt(1)
	v_mfma_f32_32x32x16_bf16 v[112:127], v[220:223], v[224:227], v[112:127]
	v_mfma_f32_32x32x16_bf16 v[96:111], v[234:237], v[224:227], v[96:111]
	ds_read_b128 v[224:227], v191 offset:9312
	s_waitcnt lgkmcnt(1)
	v_mfma_f32_32x32x16_bf16 v[80:95], v[220:223], v[248:251], v[80:95]
	v_mfma_f32_32x32x16_bf16 v[64:79], v[234:237], v[248:251], v[64:79]
	ds_read_b128 v[248:251], v191 offset:13920
	s_waitcnt lgkmcnt(1)
	v_mfma_f32_32x32x16_bf16 v[48:63], v[220:223], v[224:227], v[48:63]
	v_mfma_f32_32x32x16_bf16 v[32:47], v[234:237], v[224:227], v[32:47]
	s_waitcnt lgkmcnt(0)
	s_barrier
	v_mfma_f32_32x32x16_bf16 v[16:31], v[220:223], v[248:251], v[16:31]
	v_mfma_f32_32x32x16_bf16 v[0:15], v[234:237], v[248:251], v[0:15]
	s_cbranch_scc1 .LBB0_956

; #define MFMA(a, b, c) __builtin_amdgcn_mfma_f32_32x32x16_bf16((a), (b), (c), 0, 0, 0)
; template <int AMODE, int BN, class Epi>
; __device__ __forceinline__ void gemm_tile(const bf16_t* A, const int lda, const bf16_t* Bt, const int K, const int m0, const float* mu, char* lds, const Epi& epi) {
;     ...
;   for (int kt = 0; kt < nk; ++kt) {
;     const int s = kt & 1;
;     if (kt + 1 < nk) lstore(s ^ 1, (kt + 1) * 64);
;     if (kt + 2 < nk) gload((kt + 2) * 64);
;     {
;       const char* Ab = lds + s * G_STAGE + (wm * (32 * MI) + r32) * G_LDT + hi * 16;
;       const char* Bb = lds + s * G_STAGE + 256 * G_LDT + (wn * 64 + r32) * G_LDT + hi * 16;
;       bf16x8 fb[2][2], fa[2][MI];
;       fb[0][0] = *(const bf16x8*)(Bb); fb[0][1] = *(const bf16x8*)(Bb + 32 * G_LDT);
; #pragma unroll
;       for (int mi = 0; mi < MI; ++mi) fa[0][mi] = *(const bf16x8*)(Ab + mi * 32 * G_LDT);
; #pragma unroll
;       for (int ks = 0; ks < 4; ++ks) {
;         const int sl = ks & 1;
;         if (ks + 1 < 4) {
;           fb[sl ^ 1][0] = *(const bf16x8*)(Bb + (ks + 1) * 32); fb[sl ^ 1][1] = *(const bf16x8*)(Bb + 32 * G_LDT + (ks + 1) * 32);
; #pragma unroll
;           for (int mi = 0; mi < MI; ++mi) fa[sl ^ 1][mi] = *(const bf16x8*)(Ab + mi * 32 * G_LDT + (ks + 1) * 32);
;         }
; #pragma unroll
;         for (int mi = 0; mi < MI; ++mi) { acc[mi][0] = MFMA(fb[sl][0], fa[sl][mi], acc[mi][0]); acc[mi][1] = MFMA(fb[sl][1], fa[sl][mi], acc[mi][1]); }
;       }
;     }
;     __syncthreads();
;   }
.LBB0_968:
	s_mul_i32 s17, s17, 0x12000
	s_add_i32 s17, s17, 0
	v_add3_u32 v181, s17, v216, v215
	v_add3_u32 v187, s17, v214, v215
	s_add_u32 s10, s10, 0x80
	s_addc_u32 s11, s11, 0
	s_add_i32 s6, s6, 1
	s_cmpk_eq_i32 s10, 0x200
	ds_read_b128 v[234:237], v181 offset:36864
	ds_read_b128 v[242:245], v181 offset:41472
	ds_read_b128 v[238:241], v187
	ds_read_b128 v[248:251], v187 offset:4608
	s_waitcnt lgkmcnt(1)
	v_mfma_f32_32x32x16_bf16 v[112:127], v[234:237], v[238:241], v[112:127]
	v_mfma_f32_32x32x16_bf16 v[96:111], v[242:245], v[238:241], v[96:111]
	ds_read_b128 v[238:241], v187 offset:9216
	s_waitcnt lgkmcnt(1)
	v_mfma_f32_32x32x16_bf16 v[80:95], v[234:237], v[248:251], v[80:95]
	v_mfma_f32_32x32x16_bf16 v[64:79], v[242:245], v[248:251], v[64:79]
	ds_read_b128 v[248:251], v187 offset:13824
	s_waitcnt lgkmcnt(1)
	v_mfma_f32_32x32x16_bf16 v[48:63], v[234:237], v[238:241], v[48:63]
	v_mfma_f32_32x32x16_bf16 v[32:47], v[242:245], v[238:241], v[32:47]
	ds_read_b128 v[238:241], v187 offset:32
	s_waitcnt lgkmcnt(1)
	v_mfma_f32_32x32x16_bf16 v[16:31], v[234:237], v[248:251], v[16:31]
	v_mfma_f32_32x32x16_bf16 v[0:15], v[242:245], v[248:251], v[0:15]
	ds_read_b128 v[234:237], v181 offset:36896
	ds_read_b128 v[242:245], v181 offset:41504
	ds_read_b128 v[248:251], v187 offset:4640
	s_waitcnt lgkmcnt(1)
	v_mfma_f32_32x32x16_bf16 v[112:127], v[234:237], v[238:241], v[112:127]
	v_mfma_f32_32x32x16_bf16 v[96:111], v[242:245], v[238:241], v[96:111]
	ds_read_b128 v[238:241], v187 offset:9248
	s_waitcnt lgkmcnt(1)
	v_mfma_f32_32x32x16_bf16 v[80:95], v[234:237], v[248:251], v[80:95]
	v_mfma_f32_32x32x16_bf16 v[64:79], v[242:245], v[248:251], v[64:79]
	ds_read_b128 v[248:251], v187 offset:13856
	s_waitcnt lgkmcnt(1)
	v_mfma_f32_32x32x16_bf16 v[48:63], v[234:237], v[238:241], v[48:63]
	v_mfma_f32_32x32x16_bf16 v[32:47], v[242:245], v[238:241], v[32:47]
	ds_read_b128 v[238:241], v187 offset:64
	s_waitcnt lgkmcnt(1)
	v_mfma_f32_32x32x16_bf16 v[16:31], v[234:237], v[248:251], v[16:31]
	v_mfma_f32_32x32x16_bf16 v[0:15], v[242:245], v[248:251], v[0:15]
	ds_read_b128 v[234:237], v181 offset:36928
	ds_read_b128 v[242:245], v181 offset:41536
	ds_read_b128 v[248:251], v187 offset:4672
	s_waitcnt lgkmcnt(1)
	v_mfma_f32_32x32x16_bf16 v[112:127], v[234:237], v[238:241], v[112:127]
	v_mfma_f32_32x32x16_bf16 v[96:111], v[242:245], v[238:241], v[96:111]
	ds_read_b128 v[238:241], v187 offset:9280
	s_waitcnt lgkmcnt(1)
	v_mfma_f32_32x32x16_bf16 v[80:95], v[234:237], v[248:251], v[80:95]
	v_mfma_f32_32x32x16_bf16 v[64:79], v[242:245], v[248:251], v[64:79]
	ds_read_b128 v[248:251], v187 offset:13888
	s_waitcnt lgkmcnt(1)
	v_mfma_f32_32x32x16_bf16 v[48:63], v[234:237], v[238:241], v[48:63]
	v_mfma_f32_32x32x16_bf16 v[32:47], v[242:245], v[238:241], v[32:47]
	ds_read_b128 v[238:241], v187 offset:96
	s_waitcnt lgkmcnt(1)
	v_mfma_f32_32x32x16_bf16 v[16:31], v[234:237], v[248:251], v[16:31]
	v_mfma_f32_32x32x16_bf16 v[0:15], v[242:245], v[248:251], v[0:15]
	ds_read_b128 v[234:237], v181 offset:36960
	ds_read_b128 v[242:245], v181 offset:41568
	ds_read_b128 v[248:251], v187 offset:4704
	s_waitcnt lgkmcnt(1)
	v_mfma_f32_32x32x16_bf16 v[112:127], v[234:237], v[238:241], v[112:127]
	v_mfma_f32_32x32x16_bf16 v[96:111], v[242:245], v[238:241], v[96:111]
	ds_read_b128 v[238:241], v187 offset:9312
	s_waitcnt lgkmcnt(1)
	v_mfma_f32_32x32x16_bf16 v[80:95], v[234:237], v[248:251], v[80:95]
	v_mfma_f32_32x32x16_bf16 v[64:79], v[242:245], v[248:251], v[64:79]
	ds_read_b128 v[248:251], v187 offset:13920
	s_waitcnt lgkmcnt(1)
	v_mfma_f32_32x32x16_bf16 v[48:63], v[234:237], v[238:241], v[48:63]
	v_mfma_f32_32x32x16_bf16 v[32:47], v[242:245], v[238:241], v[32:47]
	s_waitcnt lgkmcnt(0)
	s_barrier
	v_mfma_f32_32x32x16_bf16 v[16:31], v[234:237], v[248:251], v[16:31]
	v_mfma_f32_32x32x16_bf16 v[0:15], v[242:245], v[248:251], v[0:15]
	s_cbranch_scc1 .LBB0_973
